# SwiGLU epilogue hand-rewritten with packed f32 math, batched exp/rcp, in-place accumulators (half the VALU instructions)
# speedup vs baseline: 1.0124x; 1.0124x over previous
.LBB0_1087:
	v_readfirstlane_b32 s2, v179
	s_lshl_b32 s0, s8, 8
	s_ashr_i32 s1, s2, 2
	s_andn2_b32 s1, s1, 63
	s_add_i32 s1, s1, s0
	v_and_or_b32 v184, v179, 15, s1
	v_ashrrev_i32_e32 v185, 31, v184
	v_lshl_add_u64 v[128:129], v[184:185], 4, s[24:25]
	global_load_dwordx4 v[190:193], v[128:129], off
	global_load_dwordx4 v[194:197], v[128:129], off offset:256
	global_load_dwordx4 v[198:201], v[128:129], off offset:512
	global_load_dwordx4 v[214:217], v[128:129], off offset:768
	global_load_dwordx4 v[140:143], v[128:129], off offset:2048
	global_load_dwordx4 v[136:139], v[128:129], off offset:2304
	global_load_dwordx4 v[132:135], v[128:129], off offset:2560
	global_load_dwordx4 v[156:159], v[128:129], off offset:2816
	s_movk_i32 s8, 0x1600
	v_mov_b64_e32 v[186:187], s[42:43]
	s_lshl_b32 s0, s33, 8
	s_and_b32 s1, s2, 0xc0
	v_mad_i64_i32 v[186:187], s[4:5], v184, s8, v[186:187]
	s_add_i32 s0, s0, s1
	v_and_b32_e32 v176, 48, v179
	v_add_u32_e32 v176, s0, v176
	v_mov_b32_e32 v188, 0x358637bd
	v_lshl_add_u64 v[186:187], v[186:187], 0, v[176:177]
	s_mov_b32 s0, 0x3a800000
	s_mov_b32 s2, 0xbfb8aa3b
	s_waitcnt vmcnt(0)
	v_add_f32_e32 v190, v190, v191
	v_add_f32_e32 v192, v192, v193
	v_add_f32_e32 v194, v194, v195
	v_add_f32_e32 v196, v196, v197
	v_add_f32_e32 v198, v198, v199
	v_add_f32_e32 v200, v200, v201
	v_add_f32_e32 v214, v214, v215
	v_add_f32_e32 v216, v216, v217
	v_add_f32_e32 v140, v140, v141
	v_add_f32_e32 v142, v142, v143
	v_add_f32_e32 v136, v136, v137
	v_add_f32_e32 v138, v138, v139
	v_add_f32_e32 v132, v132, v133
	v_add_f32_e32 v134, v134, v135
	v_add_f32_e32 v156, v156, v157
	v_add_f32_e32 v158, v158, v159
	v_add_f32_e32 v190, v190, v192
	v_add_f32_e32 v194, v194, v196
	v_add_f32_e32 v198, v198, v200
	v_add_f32_e32 v214, v214, v216
	v_add_f32_e32 v140, v140, v142
	v_add_f32_e32 v136, v136, v138
	v_add_f32_e32 v132, v132, v134
	v_add_f32_e32 v156, v156, v158
	v_fma_f32 v190, v190, s0, v188
	v_fma_f32 v194, v194, s0, v188
	v_fma_f32 v198, v198, s0, v188
	v_fma_f32 v214, v214, s0, v188
	v_fma_f32 v140, v140, s0, v188
	v_fma_f32 v136, v136, s0, v188
	v_fma_f32 v132, v132, s0, v188
	v_fma_f32 v156, v156, s0, v188
	v_rsq_f32_e32 v160, v190
	v_rsq_f32_e32 v162, v194
	v_rsq_f32_e32 v164, v198
	v_rsq_f32_e32 v166, v214
	v_rsq_f32_e32 v168, v140
	v_rsq_f32_e32 v170, v136
	v_rsq_f32_e32 v172, v132
	v_rsq_f32_e32 v174, v156
	s_mov_b32 s0, 1.0
	v_pk_mul_f32 v[124:125], v[124:125], v[160:161] op_sel_hi:[1,0]
	v_pk_mul_f32 v[126:127], v[126:127], v[160:161] op_sel_hi:[1,0]
	v_pk_mul_f32 v[116:117], v[116:117], v[160:161] op_sel_hi:[1,0]
	v_pk_mul_f32 v[118:119], v[118:119], v[160:161] op_sel_hi:[1,0]
	v_pk_mul_f32 v[120:121], v[120:121], v[160:161] op_sel_hi:[1,0]
	v_pk_mul_f32 v[122:123], v[122:123], v[160:161] op_sel_hi:[1,0]
	v_pk_mul_f32 v[112:113], v[112:113], v[160:161] op_sel_hi:[1,0]
	v_pk_mul_f32 v[114:115], v[114:115], v[160:161] op_sel_hi:[1,0]
	v_pk_mul_f32 v[120:121], v[124:125], v[120:121]
	v_pk_mul_f32 v[122:123], v[126:127], v[122:123]
	v_pk_mul_f32 v[112:113], v[116:117], v[112:113]
	v_pk_mul_f32 v[114:115], v[118:119], v[114:115]
	v_pk_mul_f32 v[124:125], v[124:125], s[2:3] op_sel_hi:[1,0]
	v_pk_mul_f32 v[126:127], v[126:127], s[2:3] op_sel_hi:[1,0]
	v_pk_mul_f32 v[116:117], v[116:117], s[2:3] op_sel_hi:[1,0]
	v_pk_mul_f32 v[118:119], v[118:119], s[2:3] op_sel_hi:[1,0]
	v_exp_f32_e32 v124, v124
	v_exp_f32_e32 v125, v125
	v_exp_f32_e32 v126, v126
	v_exp_f32_e32 v127, v127
	v_exp_f32_e32 v116, v116
	v_exp_f32_e32 v117, v117
	v_exp_f32_e32 v118, v118
	v_exp_f32_e32 v119, v119
	v_pk_add_f32 v[124:125], v[124:125], s[0:1] op_sel_hi:[1,0]
	v_pk_add_f32 v[126:127], v[126:127], s[0:1] op_sel_hi:[1,0]
	v_pk_add_f32 v[116:117], v[116:117], s[0:1] op_sel_hi:[1,0]
	v_pk_add_f32 v[118:119], v[118:119], s[0:1] op_sel_hi:[1,0]
	v_rcp_f32_e32 v124, v124
	v_rcp_f32_e32 v125, v125
	v_rcp_f32_e32 v126, v126
	v_rcp_f32_e32 v127, v127
	v_rcp_f32_e32 v116, v116
	v_rcp_f32_e32 v117, v117
	v_rcp_f32_e32 v118, v118
	v_rcp_f32_e32 v119, v119
	v_pk_mul_f32 v[120:121], v[120:121], v[124:125]
	v_pk_mul_f32 v[122:123], v[122:123], v[126:127]
	v_pk_mul_f32 v[112:113], v[112:113], v[116:117]
	v_pk_mul_f32 v[114:115], v[114:115], v[118:119]
	v_cvt_pk_bf16_f32 v124, v120, v121
	v_cvt_pk_bf16_f32 v125, v122, v123
	v_cvt_pk_bf16_f32 v126, v112, v113
	v_cvt_pk_bf16_f32 v127, v114, v115
	global_store_dwordx4 v[186:187], v[124:127], off
	v_pk_mul_f32 v[108:109], v[108:109], v[162:163] op_sel_hi:[1,0]
	v_pk_mul_f32 v[110:111], v[110:111], v[162:163] op_sel_hi:[1,0]
	v_pk_mul_f32 v[100:101], v[100:101], v[162:163] op_sel_hi:[1,0]
	v_pk_mul_f32 v[102:103], v[102:103], v[162:163] op_sel_hi:[1,0]
	v_pk_mul_f32 v[104:105], v[104:105], v[162:163] op_sel_hi:[1,0]
	v_pk_mul_f32 v[106:107], v[106:107], v[162:163] op_sel_hi:[1,0]
	v_pk_mul_f32 v[96:97], v[96:97], v[162:163] op_sel_hi:[1,0]
	v_pk_mul_f32 v[98:99], v[98:99], v[162:163] op_sel_hi:[1,0]
	v_pk_mul_f32 v[104:105], v[108:109], v[104:105]
	v_pk_mul_f32 v[106:107], v[110:111], v[106:107]
	v_pk_mul_f32 v[96:97], v[100:101], v[96:97]
	v_pk_mul_f32 v[98:99], v[102:103], v[98:99]
	v_pk_mul_f32 v[108:109], v[108:109], s[2:3] op_sel_hi:[1,0]
	v_pk_mul_f32 v[110:111], v[110:111], s[2:3] op_sel_hi:[1,0]
	v_pk_mul_f32 v[100:101], v[100:101], s[2:3] op_sel_hi:[1,0]
	v_pk_mul_f32 v[102:103], v[102:103], s[2:3] op_sel_hi:[1,0]
	v_exp_f32_e32 v108, v108
	v_exp_f32_e32 v109, v109
	v_exp_f32_e32 v110, v110
	v_exp_f32_e32 v111, v111
	v_exp_f32_e32 v100, v100
	v_exp_f32_e32 v101, v101
	v_exp_f32_e32 v102, v102
	v_exp_f32_e32 v103, v103
	v_pk_add_f32 v[108:109], v[108:109], s[0:1] op_sel_hi:[1,0]
	v_pk_add_f32 v[110:111], v[110:111], s[0:1] op_sel_hi:[1,0]
	v_pk_add_f32 v[100:101], v[100:101], s[0:1] op_sel_hi:[1,0]
	v_pk_add_f32 v[102:103], v[102:103], s[0:1] op_sel_hi:[1,0]
	v_rcp_f32_e32 v108, v108
	v_rcp_f32_e32 v109, v109
	v_rcp_f32_e32 v110, v110
	v_rcp_f32_e32 v111, v111
	v_rcp_f32_e32 v100, v100
	v_rcp_f32_e32 v101, v101
	v_rcp_f32_e32 v102, v102
	v_rcp_f32_e32 v103, v103
	s_mov_b64 s[4:5], 0x16000
	v_lshl_add_u64 v[130:131], v[186:187], 0, s[4:5]
	v_pk_mul_f32 v[104:105], v[104:105], v[108:109]
	v_pk_mul_f32 v[106:107], v[106:107], v[110:111]
	v_pk_mul_f32 v[96:97], v[96:97], v[100:101]
	v_pk_mul_f32 v[98:99], v[98:99], v[102:103]
	v_cvt_pk_bf16_f32 v108, v104, v105
	v_cvt_pk_bf16_f32 v109, v106, v107
	v_cvt_pk_bf16_f32 v110, v96, v97
	v_cvt_pk_bf16_f32 v111, v98, v99
	global_store_dwordx4 v[130:131], v[108:111], off
	v_pk_mul_f32 v[92:93], v[92:93], v[164:165] op_sel_hi:[1,0]
	v_pk_mul_f32 v[94:95], v[94:95], v[164:165] op_sel_hi:[1,0]
	v_pk_mul_f32 v[84:85], v[84:85], v[164:165] op_sel_hi:[1,0]
	v_pk_mul_f32 v[86:87], v[86:87], v[164:165] op_sel_hi:[1,0]
	v_pk_mul_f32 v[88:89], v[88:89], v[164:165] op_sel_hi:[1,0]
	v_pk_mul_f32 v[90:91], v[90:91], v[164:165] op_sel_hi:[1,0]
	v_pk_mul_f32 v[80:81], v[80:81], v[164:165] op_sel_hi:[1,0]
	v_pk_mul_f32 v[82:83], v[82:83], v[164:165] op_sel_hi:[1,0]
	v_pk_mul_f32 v[88:89], v[92:93], v[88:89]
	v_pk_mul_f32 v[90:91], v[94:95], v[90:91]
	v_pk_mul_f32 v[80:81], v[84:85], v[80:81]
	v_pk_mul_f32 v[82:83], v[86:87], v[82:83]
	v_pk_mul_f32 v[92:93], v[92:93], s[2:3] op_sel_hi:[1,0]
	v_pk_mul_f32 v[94:95], v[94:95], s[2:3] op_sel_hi:[1,0]
	v_pk_mul_f32 v[84:85], v[84:85], s[2:3] op_sel_hi:[1,0]
	v_pk_mul_f32 v[86:87], v[86:87], s[2:3] op_sel_hi:[1,0]
	v_exp_f32_e32 v92, v92
	v_exp_f32_e32 v93, v93
	v_exp_f32_e32 v94, v94
	v_exp_f32_e32 v95, v95
	v_exp_f32_e32 v84, v84
	v_exp_f32_e32 v85, v85
	v_exp_f32_e32 v86, v86
	v_exp_f32_e32 v87, v87
	v_pk_add_f32 v[92:93], v[92:93], s[0:1] op_sel_hi:[1,0]
	v_pk_add_f32 v[94:95], v[94:95], s[0:1] op_sel_hi:[1,0]
	v_pk_add_f32 v[84:85], v[84:85], s[0:1] op_sel_hi:[1,0]
	v_pk_add_f32 v[86:87], v[86:87], s[0:1] op_sel_hi:[1,0]
	v_rcp_f32_e32 v92, v92
	v_rcp_f32_e32 v93, v93
	v_rcp_f32_e32 v94, v94
	v_rcp_f32_e32 v95, v95
	v_rcp_f32_e32 v84, v84
	v_rcp_f32_e32 v85, v85
	v_rcp_f32_e32 v86, v86
	v_rcp_f32_e32 v87, v87
	s_mov_b64 s[4:5], 0x2c000
	v_lshl_add_u64 v[128:129], v[186:187], 0, s[4:5]
	v_pk_mul_f32 v[88:89], v[88:89], v[92:93]
	v_pk_mul_f32 v[90:91], v[90:91], v[94:95]
	v_pk_mul_f32 v[80:81], v[80:81], v[84:85]
	v_pk_mul_f32 v[82:83], v[82:83], v[86:87]
	v_cvt_pk_bf16_f32 v92, v88, v89
	v_cvt_pk_bf16_f32 v93, v90, v91
	v_cvt_pk_bf16_f32 v94, v80, v81
	v_cvt_pk_bf16_f32 v95, v82, v83
	global_store_dwordx4 v[128:129], v[92:95], off
	v_pk_mul_f32 v[76:77], v[76:77], v[166:167] op_sel_hi:[1,0]
	v_pk_mul_f32 v[78:79], v[78:79], v[166:167] op_sel_hi:[1,0]
	v_pk_mul_f32 v[68:69], v[68:69], v[166:167] op_sel_hi:[1,0]
	v_pk_mul_f32 v[70:71], v[70:71], v[166:167] op_sel_hi:[1,0]
	v_pk_mul_f32 v[72:73], v[72:73], v[166:167] op_sel_hi:[1,0]
	v_pk_mul_f32 v[74:75], v[74:75], v[166:167] op_sel_hi:[1,0]
	v_pk_mul_f32 v[64:65], v[64:65], v[166:167] op_sel_hi:[1,0]
	v_pk_mul_f32 v[66:67], v[66:67], v[166:167] op_sel_hi:[1,0]
	v_pk_mul_f32 v[72:73], v[76:77], v[72:73]
	v_pk_mul_f32 v[74:75], v[78:79], v[74:75]
	v_pk_mul_f32 v[64:65], v[68:69], v[64:65]
	v_pk_mul_f32 v[66:67], v[70:71], v[66:67]
	v_pk_mul_f32 v[76:77], v[76:77], s[2:3] op_sel_hi:[1,0]
	v_pk_mul_f32 v[78:79], v[78:79], s[2:3] op_sel_hi:[1,0]
	v_pk_mul_f32 v[68:69], v[68:69], s[2:3] op_sel_hi:[1,0]
	v_pk_mul_f32 v[70:71], v[70:71], s[2:3] op_sel_hi:[1,0]
	v_exp_f32_e32 v76, v76
	v_exp_f32_e32 v77, v77
	v_exp_f32_e32 v78, v78
	v_exp_f32_e32 v79, v79
	v_exp_f32_e32 v68, v68
	v_exp_f32_e32 v69, v69
	v_exp_f32_e32 v70, v70
	v_exp_f32_e32 v71, v71
	v_pk_add_f32 v[76:77], v[76:77], s[0:1] op_sel_hi:[1,0]
	v_pk_add_f32 v[78:79], v[78:79], s[0:1] op_sel_hi:[1,0]
	v_pk_add_f32 v[68:69], v[68:69], s[0:1] op_sel_hi:[1,0]
	v_pk_add_f32 v[70:71], v[70:71], s[0:1] op_sel_hi:[1,0]
	v_rcp_f32_e32 v76, v76
	v_rcp_f32_e32 v77, v77
	v_rcp_f32_e32 v78, v78
	v_rcp_f32_e32 v79, v79
	v_rcp_f32_e32 v68, v68
	v_rcp_f32_e32 v69, v69
	v_rcp_f32_e32 v70, v70
	v_rcp_f32_e32 v71, v71
	s_mov_b64 s[4:5], 0x42000
	v_lshl_add_u64 v[130:131], v[186:187], 0, s[4:5]
	v_pk_mul_f32 v[72:73], v[72:73], v[76:77]
	v_pk_mul_f32 v[74:75], v[74:75], v[78:79]
	v_pk_mul_f32 v[64:65], v[64:65], v[68:69]
	v_pk_mul_f32 v[66:67], v[66:67], v[70:71]
	v_cvt_pk_bf16_f32 v76, v72, v73
	v_cvt_pk_bf16_f32 v77, v74, v75
	v_cvt_pk_bf16_f32 v78, v64, v65
	v_cvt_pk_bf16_f32 v79, v66, v67
	global_store_dwordx4 v[130:131], v[76:79], off
	v_pk_mul_f32 v[60:61], v[60:61], v[168:169] op_sel_hi:[1,0]
	v_pk_mul_f32 v[62:63], v[62:63], v[168:169] op_sel_hi:[1,0]
	v_pk_mul_f32 v[52:53], v[52:53], v[168:169] op_sel_hi:[1,0]
	v_pk_mul_f32 v[54:55], v[54:55], v[168:169] op_sel_hi:[1,0]
	v_pk_mul_f32 v[56:57], v[56:57], v[168:169] op_sel_hi:[1,0]
	v_pk_mul_f32 v[58:59], v[58:59], v[168:169] op_sel_hi:[1,0]
	v_pk_mul_f32 v[48:49], v[48:49], v[168:169] op_sel_hi:[1,0]
	v_pk_mul_f32 v[50:51], v[50:51], v[168:169] op_sel_hi:[1,0]
	v_pk_mul_f32 v[56:57], v[60:61], v[56:57]
	v_pk_mul_f32 v[58:59], v[62:63], v[58:59]
	v_pk_mul_f32 v[48:49], v[52:53], v[48:49]
	v_pk_mul_f32 v[50:51], v[54:55], v[50:51]
	v_pk_mul_f32 v[60:61], v[60:61], s[2:3] op_sel_hi:[1,0]
	v_pk_mul_f32 v[62:63], v[62:63], s[2:3] op_sel_hi:[1,0]
	v_pk_mul_f32 v[52:53], v[52:53], s[2:3] op_sel_hi:[1,0]
	v_pk_mul_f32 v[54:55], v[54:55], s[2:3] op_sel_hi:[1,0]
	v_exp_f32_e32 v60, v60
	v_exp_f32_e32 v61, v61
	v_exp_f32_e32 v62, v62
	v_exp_f32_e32 v63, v63
	v_exp_f32_e32 v52, v52
	v_exp_f32_e32 v53, v53
	v_exp_f32_e32 v54, v54
	v_exp_f32_e32 v55, v55
	v_pk_add_f32 v[60:61], v[60:61], s[0:1] op_sel_hi:[1,0]
	v_pk_add_f32 v[62:63], v[62:63], s[0:1] op_sel_hi:[1,0]
	v_pk_add_f32 v[52:53], v[52:53], s[0:1] op_sel_hi:[1,0]
	v_pk_add_f32 v[54:55], v[54:55], s[0:1] op_sel_hi:[1,0]
	v_rcp_f32_e32 v60, v60
	v_rcp_f32_e32 v61, v61
	v_rcp_f32_e32 v62, v62
	v_rcp_f32_e32 v63, v63
	v_rcp_f32_e32 v52, v52
	v_rcp_f32_e32 v53, v53
	v_rcp_f32_e32 v54, v54
	v_rcp_f32_e32 v55, v55
	s_mov_b64 s[4:5], 0xb0000
	v_lshl_add_u64 v[128:129], v[186:187], 0, s[4:5]
	v_pk_mul_f32 v[56:57], v[56:57], v[60:61]
	v_pk_mul_f32 v[58:59], v[58:59], v[62:63]
	v_pk_mul_f32 v[48:49], v[48:49], v[52:53]
	v_pk_mul_f32 v[50:51], v[50:51], v[54:55]
	v_cvt_pk_bf16_f32 v60, v56, v57
	v_cvt_pk_bf16_f32 v61, v58, v59
	v_cvt_pk_bf16_f32 v62, v48, v49
	v_cvt_pk_bf16_f32 v63, v50, v51
	global_store_dwordx4 v[128:129], v[60:63], off
	v_pk_mul_f32 v[44:45], v[44:45], v[170:171] op_sel_hi:[1,0]
	v_pk_mul_f32 v[46:47], v[46:47], v[170:171] op_sel_hi:[1,0]
	v_pk_mul_f32 v[36:37], v[36:37], v[170:171] op_sel_hi:[1,0]
	v_pk_mul_f32 v[38:39], v[38:39], v[170:171] op_sel_hi:[1,0]
	v_pk_mul_f32 v[40:41], v[40:41], v[170:171] op_sel_hi:[1,0]
	v_pk_mul_f32 v[42:43], v[42:43], v[170:171] op_sel_hi:[1,0]
	v_pk_mul_f32 v[32:33], v[32:33], v[170:171] op_sel_hi:[1,0]
	v_pk_mul_f32 v[34:35], v[34:35], v[170:171] op_sel_hi:[1,0]
	v_pk_mul_f32 v[40:41], v[44:45], v[40:41]
	v_pk_mul_f32 v[42:43], v[46:47], v[42:43]
	v_pk_mul_f32 v[32:33], v[36:37], v[32:33]
	v_pk_mul_f32 v[34:35], v[38:39], v[34:35]
	v_pk_mul_f32 v[44:45], v[44:45], s[2:3] op_sel_hi:[1,0]
	v_pk_mul_f32 v[46:47], v[46:47], s[2:3] op_sel_hi:[1,0]
	v_pk_mul_f32 v[36:37], v[36:37], s[2:3] op_sel_hi:[1,0]
	v_pk_mul_f32 v[38:39], v[38:39], s[2:3] op_sel_hi:[1,0]
	v_exp_f32_e32 v44, v44
	v_exp_f32_e32 v45, v45
	v_exp_f32_e32 v46, v46
	v_exp_f32_e32 v47, v47
	v_exp_f32_e32 v36, v36
	v_exp_f32_e32 v37, v37
	v_exp_f32_e32 v38, v38
	v_exp_f32_e32 v39, v39
	v_pk_add_f32 v[44:45], v[44:45], s[0:1] op_sel_hi:[1,0]
	v_pk_add_f32 v[46:47], v[46:47], s[0:1] op_sel_hi:[1,0]
	v_pk_add_f32 v[36:37], v[36:37], s[0:1] op_sel_hi:[1,0]
	v_pk_add_f32 v[38:39], v[38:39], s[0:1] op_sel_hi:[1,0]
	v_rcp_f32_e32 v44, v44
	v_rcp_f32_e32 v45, v45
	v_rcp_f32_e32 v46, v46
	v_rcp_f32_e32 v47, v47
	v_rcp_f32_e32 v36, v36
	v_rcp_f32_e32 v37, v37
	v_rcp_f32_e32 v38, v38
	v_rcp_f32_e32 v39, v39
	s_mov_b64 s[4:5], 0xc6000
	v_lshl_add_u64 v[130:131], v[186:187], 0, s[4:5]
	v_pk_mul_f32 v[40:41], v[40:41], v[44:45]
	v_pk_mul_f32 v[42:43], v[42:43], v[46:47]
	v_pk_mul_f32 v[32:33], v[32:33], v[36:37]
	v_pk_mul_f32 v[34:35], v[34:35], v[38:39]
	v_cvt_pk_bf16_f32 v44, v40, v41
	v_cvt_pk_bf16_f32 v45, v42, v43
	v_cvt_pk_bf16_f32 v46, v32, v33
	v_cvt_pk_bf16_f32 v47, v34, v35
	global_store_dwordx4 v[130:131], v[44:47], off
	v_pk_mul_f32 v[28:29], v[28:29], v[172:173] op_sel_hi:[1,0]
	v_pk_mul_f32 v[30:31], v[30:31], v[172:173] op_sel_hi:[1,0]
	v_pk_mul_f32 v[20:21], v[20:21], v[172:173] op_sel_hi:[1,0]
	v_pk_mul_f32 v[22:23], v[22:23], v[172:173] op_sel_hi:[1,0]
	v_pk_mul_f32 v[24:25], v[24:25], v[172:173] op_sel_hi:[1,0]
	v_pk_mul_f32 v[26:27], v[26:27], v[172:173] op_sel_hi:[1,0]
	v_pk_mul_f32 v[16:17], v[16:17], v[172:173] op_sel_hi:[1,0]
	v_pk_mul_f32 v[18:19], v[18:19], v[172:173] op_sel_hi:[1,0]
	v_pk_mul_f32 v[24:25], v[28:29], v[24:25]
	v_pk_mul_f32 v[26:27], v[30:31], v[26:27]
	v_pk_mul_f32 v[16:17], v[20:21], v[16:17]
	v_pk_mul_f32 v[18:19], v[22:23], v[18:19]
	v_pk_mul_f32 v[28:29], v[28:29], s[2:3] op_sel_hi:[1,0]
	v_pk_mul_f32 v[30:31], v[30:31], s[2:3] op_sel_hi:[1,0]
	v_pk_mul_f32 v[20:21], v[20:21], s[2:3] op_sel_hi:[1,0]
	v_pk_mul_f32 v[22:23], v[22:23], s[2:3] op_sel_hi:[1,0]
	v_exp_f32_e32 v28, v28
	v_exp_f32_e32 v29, v29
	v_exp_f32_e32 v30, v30
	v_exp_f32_e32 v31, v31
	v_exp_f32_e32 v20, v20
	v_exp_f32_e32 v21, v21
	v_exp_f32_e32 v22, v22
	v_exp_f32_e32 v23, v23
	v_pk_add_f32 v[28:29], v[28:29], s[0:1] op_sel_hi:[1,0]
	v_pk_add_f32 v[30:31], v[30:31], s[0:1] op_sel_hi:[1,0]
	v_pk_add_f32 v[20:21], v[20:21], s[0:1] op_sel_hi:[1,0]
	v_pk_add_f32 v[22:23], v[22:23], s[0:1] op_sel_hi:[1,0]
	v_rcp_f32_e32 v28, v28
	v_rcp_f32_e32 v29, v29
	v_rcp_f32_e32 v30, v30
	v_rcp_f32_e32 v31, v31
	v_rcp_f32_e32 v20, v20
	v_rcp_f32_e32 v21, v21
	v_rcp_f32_e32 v22, v22
	v_rcp_f32_e32 v23, v23
	s_mov_b64 s[4:5], 0xdc000
	v_lshl_add_u64 v[128:129], v[186:187], 0, s[4:5]
	v_pk_mul_f32 v[24:25], v[24:25], v[28:29]
	v_pk_mul_f32 v[26:27], v[26:27], v[30:31]
	v_pk_mul_f32 v[16:17], v[16:17], v[20:21]
	v_pk_mul_f32 v[18:19], v[18:19], v[22:23]
	v_cvt_pk_bf16_f32 v28, v24, v25
	v_cvt_pk_bf16_f32 v29, v26, v27
	v_cvt_pk_bf16_f32 v30, v16, v17
	v_cvt_pk_bf16_f32 v31, v18, v19
	global_store_dwordx4 v[128:129], v[28:31], off
	v_pk_mul_f32 v[12:13], v[12:13], v[174:175] op_sel_hi:[1,0]
	v_pk_mul_f32 v[14:15], v[14:15], v[174:175] op_sel_hi:[1,0]
	v_pk_mul_f32 v[4:5], v[4:5], v[174:175] op_sel_hi:[1,0]
	v_pk_mul_f32 v[6:7], v[6:7], v[174:175] op_sel_hi:[1,0]
	v_pk_mul_f32 v[8:9], v[8:9], v[174:175] op_sel_hi:[1,0]
	v_pk_mul_f32 v[10:11], v[10:11], v[174:175] op_sel_hi:[1,0]
	v_pk_mul_f32 v[0:1], v[0:1], v[174:175] op_sel_hi:[1,0]
	v_pk_mul_f32 v[2:3], v[2:3], v[174:175] op_sel_hi:[1,0]
	v_pk_mul_f32 v[8:9], v[12:13], v[8:9]
	v_pk_mul_f32 v[10:11], v[14:15], v[10:11]
	v_pk_mul_f32 v[0:1], v[4:5], v[0:1]
	v_pk_mul_f32 v[2:3], v[6:7], v[2:3]
	v_pk_mul_f32 v[12:13], v[12:13], s[2:3] op_sel_hi:[1,0]
	v_pk_mul_f32 v[14:15], v[14:15], s[2:3] op_sel_hi:[1,0]
	v_pk_mul_f32 v[4:5], v[4:5], s[2:3] op_sel_hi:[1,0]
	v_pk_mul_f32 v[6:7], v[6:7], s[2:3] op_sel_hi:[1,0]
	v_exp_f32_e32 v12, v12
	v_exp_f32_e32 v13, v13
	v_exp_f32_e32 v14, v14
	v_exp_f32_e32 v15, v15
	v_exp_f32_e32 v4, v4
	v_exp_f32_e32 v5, v5
	v_exp_f32_e32 v6, v6
	v_exp_f32_e32 v7, v7
	v_pk_add_f32 v[12:13], v[12:13], s[0:1] op_sel_hi:[1,0]
	v_pk_add_f32 v[14:15], v[14:15], s[0:1] op_sel_hi:[1,0]
	v_pk_add_f32 v[4:5], v[4:5], s[0:1] op_sel_hi:[1,0]
	v_pk_add_f32 v[6:7], v[6:7], s[0:1] op_sel_hi:[1,0]
	v_rcp_f32_e32 v12, v12
	v_rcp_f32_e32 v13, v13
	v_rcp_f32_e32 v14, v14
	v_rcp_f32_e32 v15, v15
	v_rcp_f32_e32 v4, v4
	v_rcp_f32_e32 v5, v5
	v_rcp_f32_e32 v6, v6
	v_rcp_f32_e32 v7, v7
	s_mov_b64 s[4:5], 0xf2000
	v_lshl_add_u64 v[130:131], v[186:187], 0, s[4:5]
	v_pk_mul_f32 v[8:9], v[8:9], v[12:13]
	v_pk_mul_f32 v[10:11], v[10:11], v[14:15]
	v_pk_mul_f32 v[0:1], v[0:1], v[4:5]
	v_pk_mul_f32 v[2:3], v[2:3], v[6:7]
	v_cvt_pk_bf16_f32 v12, v8, v9
	v_cvt_pk_bf16_f32 v13, v10, v11
	v_cvt_pk_bf16_f32 v14, v0, v1
	v_cvt_pk_bf16_f32 v15, v2, v3
	global_store_dwordx4 v[130:131], v[12:15], off
	s_mov_b64 s[0:1], -1
	s_andn2_b64 vcc, exec, s[38:39]
	s_cbranch_vccnz .LBB0_1064
	s_andn2_b64 vcc, exec, s[40:41]
	s_cbranch_vccnz .LBB0_1063
	s_barrier
	s_branch .LBB0_1063
